# attention loop: exp2 bias -m*c kept in a register and refreshed only on the rescale path; per-half-step select+multiply+copy removed
# baseline (speedup 1.0000x reference)
; #define SBAR() __builtin_amdgcn_sched_barrier(0)
; __device__ __forceinline__ int v_st(int k, int c) { const int kk = (k & ~0xC) | ((k & 4) << 1) | ((k & 8) >> 1); return ((kk >> 3) * 4 + (c >> 5)) * 512 + ((kk & 7) * 32 + (c & 31)) * 2; }
; __device__ __forceinline__ int v_rd_base(int lane) { return ((lane & 3) << 3) | (((lane >> 2) & 3) << 6) | (((lane >> 4) & 1) << 5) | (((lane >> 5) & 1) << 8); }
; #define SLOAD_H(Kp, Vp, k0) do { S.st_v0 = load8(ROW(Vp, k0, sr)); S.st_v1 = load8(ROW(Vp, k0, 32 + sr));              \
;                          S.st_k0 = load8(ROW(Kp, k0, sr)); S.st_k1 = load8(ROW(Kp, k0, 32 + sr)); } while (0)
; #define SWRITE_HV(bf) do { *(bf16x8*)(V_lds + (bf) * SHM_V + vst0) = S.st_v0; *(bf16x8*)(V_lds + (bf) * SHM_V + vst1) = S.st_v1; } while (0)
; #define MASKT(P0_, P1_) sel_mask_tile(P0_, P1_, mw.x, mw.y, hi)
; __device__ __forceinline__ void attn_block(const BlockRef& cur, const BlockRef& nxt, char* lds, Seam& S) {
;     const int tid = threadIdx.x, wid = __builtin_amdgcn_readfirstlane(tid >> 6), lane = tid & 63, r32 = lane & 31, hi = lane >> 5;
;     const int NT = (cur.P0 + QB - 1) / KVBLK + 1;
;     char* V_lds = lds; char* K_lds = lds + 2 * SHM_V;
;     float* ws = (float*)(lds + 2 * SHM_V + 2 * SHM_K) + wid * 64; float* li_l = ws, * al_l = ws + 32;
;     float m_reg = -1e30f, l_reg = 0; f32x16 o[4] = {};
;     const int sr = tid >> 4, sc = (tid & 15) * 8, vst0 = v_st(sr, sc), vst1 = v_st(32 + sr, sc), kws = KSWZ(sr, sc * 2);
;     const int vb0 = (int)(uintptr_t)V_lds + v_rd_base(lane);
;     const bf16* Kh = cur.K; const bf16* Vh = cur.V;
;     const unsigned mrow_off = (unsigned)(wid * QBLK + r32) * 512u;
;     u32x2 mw;
;     ...
;     constexpr int NQL = 8;
;     ...
;     f32x16 pA0, pA1, pB0, pB1; float mnA, mnB, alA, alB; bf16x8 pa0, pa1, pa2, pa3;
;     SWRITE_HV(0); SBAR();
;     mw = LDMASK(0);
;     if (NT > 1) { SLOAD_H(Kh, Vh, KBASE(1)); }
;     SBAR(); qkt<0>(pA0, pA1, K_lds, r32, hi, S.qr);
;     MASKT(pA0, pA1); partialSM(pA0, pA1, m_reg, mnA, alA);
.LBB0_1298:
	v_readfirstlane_b32 s83, v0
	s_lshr_b32 s12, s38, 6
	s_or_b32 s81, s12, 3
	s_and_b32 s12, s83, 0x3fffffc0
	s_lshl_b32 s12, s12, 2
	s_add_i32 s84, s12, 0
	s_lshr_b32 s12, s83, 1
	s_and_b32 s12, s12, 0x7fffffe0
	v_and_b32_e32 v88, 31, v0
	v_or_b32_e32 v186, s12, v88
	s_mov_b32 s82, 1
	v_lshlrev_b32_e32 v165, 9, v186
	s_add_i32 s84, s84, 0x10000
	s_waitcnt vmcnt(1)
	ds_write_b128 v197, v[130:133]
	s_waitcnt vmcnt(0)
	ds_write_b128 v198, v[134:137]
	v_mov_b32_e32 v183, v167
	v_lshl_add_u64 v[2:3], s[70:71], 0, v[182:183]
	v_mov_b32_e32 v177, v167
	v_mov_b32_e32 v185, v167
	v_lshl_add_u64 v[2:3], v[2:3], 0, v[176:177]
	v_lshl_add_u64 v[4:5], s[70:71], 0, v[184:185]
	global_load_dwordx2 v[86:87], v165, s[68:69]
	v_lshl_add_u64 v[4:5], v[4:5], 0, v[176:177]
	global_load_dwordx4 v[50:53], v[2:3], off
	global_load_dwordx4 v[54:57], v[4:5], off
	v_lshl_add_u64 v[2:3], s[6:7], 0, v[182:183]
	v_lshl_add_u64 v[2:3], v[2:3], 0, v[176:177]
	v_lshl_add_u64 v[4:5], s[6:7], 0, v[184:185]
	v_lshl_add_u64 v[4:5], v[4:5], 0, v[176:177]
	global_load_dwordx4 v[58:61], v[2:3], off
	global_load_dwordx4 v[62:65], v[4:5], off
	ds_read_b128 v[2:5], v199 offset:32768
	ds_read_b128 v[6:9], v199 offset:32896
	s_mov_b32 s36, s13
	s_mov_b32 s37, s13
	s_mov_b32 s38, s13
	s_waitcnt lgkmcnt(1)
	v_mfma_f32_32x32x16_bf16 v[34:49], v[2:5], v[126:129], 0
	ds_read_b128 v[2:5], v199 offset:40960
	ds_read_b128 v[10:13], v199 offset:41088
	s_mov_b32 s39, s13
	s_mov_b32 s40, s13
	s_mov_b32 s41, s13
	s_mov_b32 s42, s13
	s_mov_b32 s43, s13
	s_mov_b32 s44, s13
	s_waitcnt lgkmcnt(1)
	v_mfma_f32_32x32x16_bf16 v[18:33], v[2:5], v[126:129], 0
	ds_read_b128 v[2:5], v200 offset:32768
	ds_read_b128 v[14:17], v200 offset:32896
	s_mov_b32 s45, s13
	s_mov_b32 s46, s13
	s_mov_b32 s47, s13
	s_mov_b32 s48, s13
	s_mov_b32 s49, s13
	s_mov_b32 s50, s13
	s_waitcnt lgkmcnt(1)
	v_mfma_f32_32x32x16_bf16 v[34:49], v[2:5], v[122:125], v[34:49]
	ds_read_b128 v[2:5], v200 offset:40960
	ds_read_b128 v[66:69], v200 offset:41088
	s_mov_b32 s51, s13
	v_lshl_add_u32 v185, v88, 2, s84
	v_lshl_add_u32 v183, v163, 2, s84
	v_add_u32_e32 v188, v170, v252
	s_mov_b64 s[16:17], s[70:71]
	s_mov_b64 s[100:101], s[6:7]
	v_mov_b32_e32 v205, 0
	s_waitcnt lgkmcnt(1)
	v_mfma_f32_32x32x16_bf16 v[18:33], v[2:5], v[122:125], v[18:33]
	ds_read_b128 v[2:5], v201 offset:32768
	ds_read_b128 v[70:73], v201 offset:32896
	s_waitcnt lgkmcnt(1)
	v_mfma_f32_32x32x16_bf16 v[34:49], v[2:5], v[118:121], v[34:49]
	ds_read_b128 v[2:5], v201 offset:40960
	ds_read_b128 v[74:77], v201 offset:41088
	s_waitcnt lgkmcnt(1)
	v_mfma_f32_32x32x16_bf16 v[18:33], v[2:5], v[118:121], v[18:33]
	ds_read_b128 v[2:5], v202 offset:32768
	ds_read_b128 v[78:81], v202 offset:32896
	s_waitcnt lgkmcnt(1)
	v_mfma_f32_32x32x16_bf16 v[34:49], v[2:5], v[114:117], v[34:49]
	ds_read_b128 v[2:5], v202 offset:40960
	ds_read_b128 v[82:85], v202 offset:41088
	s_waitcnt vmcnt(0)
	s_waitcnt vmcnt(3)
	ds_write_b128 v197, v[50:53] offset:16384
	s_waitcnt vmcnt(2)
	ds_write_b128 v198, v[54:57] offset:16384
	s_waitcnt vmcnt(1)
	ds_write_b128 v204, v[58:61] offset:49152
	s_waitcnt vmcnt(0)
	ds_write_b128 v204, v[62:65] offset:57344
	s_waitcnt lgkmcnt(0)
	s_barrier
; #define SBAR() __builtin_amdgcn_sched_barrier(0)
; __device__ __forceinline__ int v_st(int k, int c) { const int kk = (k & ~0xC) | ((k & 4) << 1) | ((k & 8) >> 1); return ((kk >> 3) * 4 + (c >> 5)) * 512 + ((kk & 7) * 32 + (c & 31)) * 2; }
; __device__ __forceinline__ int v_rd_base(int lane) { return ((lane & 3) << 3) | (((lane >> 2) & 3) << 6) | (((lane >> 4) & 1) << 5) | (((lane >> 5) & 1) << 8); }
; #define VMW() asm volatile("s_waitcnt vmcnt(0)" ::: "memory")
; __device__ __forceinline__ void partialSM(f32x16& p0, f32x16& p1, float& m_reg, float& mn, float& alpha) {
;     float pmax = p0[0];
; #pragma unroll
;     for (int r = 1; r < 16; ++r) pmax = fmaxf(pmax, p0[r]);
; #pragma unroll
;     for (int r = 0; r < 16; ++r) pmax = fmaxf(pmax, p1[r]);
;     { auto rr = __builtin_amdgcn_permlane32_swap(__float_as_uint(pmax), __float_as_uint(pmax), false, false);
;       pmax = fmaxf(__uint_as_float(rr[0]), __uint_as_float(rr[1])); }
;     constexpr float C2 = 1.4426950408889634f * SCALE;
;     if (__builtin_expect(__all((pmax - m_reg) * SCALE <= THR), 1)) { mn = m_reg; alpha = 1.f; }
;     else { mn = fmaxf(m_reg, pmax); alpha = __builtin_amdgcn_exp2f((m_reg - mn) * C2); m_reg = mn; }
;     const float mnL = -mn * C2;
; #pragma unroll
;     for (int r = 0; r < 16; ++r) p0[r] = fmaf(p0[r], C2, mnL);
; #pragma unroll
;     for (int r = 0; r < 16; ++r) p1[r] = fmaf(p1[r], C2, mnL);
; #pragma unroll
;     for (int r = 0; r < 16; ++r) p0[r] = __builtin_amdgcn_exp2f(p0[r]);
; }
; __device__ __forceinline__ void attn_block(const BlockRef& cur, const BlockRef& nxt, char* lds, Seam& S) {
;     ...
;     float m_reg = -1e30f, l_reg = 0; f32x16 o[4] = {};
;     const int sr = tid >> 4, sc = (tid & 15) * 8, vst0 = v_st(sr, sc), vst1 = v_st(32 + sr, sc), kws = KSWZ(sr, sc * 2);
;     const int vb0 = (int)(uintptr_t)V_lds + v_rd_base(lane);
;     const bf16* Kh = cur.K; const bf16* Vh = cur.V;
;     const unsigned mrow_off = (unsigned)(wid * QBLK + r32) * 512u;
;     u32x2 mw;
;     ...
;     constexpr int NQL = 8;
;     ...
;     f32x16 pA0, pA1, pB0, pB1; float mnA, mnB, alA, alB; bf16x8 pa0, pa1, pa2, pa3;
;     SWRITE_HV(0); SBAR();
;     mw = LDMASK(0);
;     if (NT > 1) { SLOAD_H(Kh, Vh, KBASE(1)); }
;     SBAR(); qkt<0>(pA0, pA1, K_lds, r32, hi, S.qr);
;     MASKT(pA0, pA1); partialSM(pA0, pA1, m_reg, mnA, alA);
;     if (NT > 1) { VMW(); SWRITE_H(1); }
;     __syncthreads();
	v_mfma_f32_32x32x16_bf16 v[34:49], v[6:9], v[110:113], v[34:49]
	v_mfma_f32_32x32x16_bf16 v[18:33], v[2:5], v[114:117], v[18:33]
	v_mfma_f32_32x32x16_bf16 v[34:49], v[14:17], v[106:109], v[34:49]
	v_mfma_f32_32x32x16_bf16 v[18:33], v[10:13], v[110:113], v[18:33]
	v_mov_b64_e32 v[2:3], s[36:37]
	v_mov_b64_e32 v[4:5], s[38:39]
	v_mov_b64_e32 v[6:7], s[40:41]
	v_mov_b64_e32 v[8:9], s[42:43]
	v_mov_b64_e32 v[10:11], s[44:45]
	v_mov_b64_e32 v[12:13], s[46:47]
	v_mov_b64_e32 v[14:15], s[48:49]
	v_mfma_f32_32x32x16_bf16 v[34:49], v[70:73], v[102:105], v[34:49]
	v_mov_b64_e32 v[16:17], s[50:51]
	v_mov_b64_e32 v[64:65], v[16:17]
	v_mov_b64_e32 v[62:63], v[14:15]
	v_mov_b64_e32 v[60:61], v[12:13]
	v_mov_b64_e32 v[58:59], v[10:11]
	v_mov_b64_e32 v[56:57], v[8:9]
	v_mov_b64_e32 v[54:55], v[6:7]
	v_mfma_f32_32x32x16_bf16 v[18:33], v[66:69], v[106:109], v[18:33]
	v_lshrrev_b32_e32 v66, v163, v86
	v_bfe_i32 v68, v66, 0, 1
	v_lshrrev_b32_e32 v67, v163, v87
	v_bfe_i32 v69, v67, 0, 1
	v_bfe_i32 v70, v67, 2, 1
	v_bfe_i32 v71, v67, 3, 1
	v_bfe_i32 v72, v67, 8, 1
	v_mfma_f32_32x32x16_bf16 v[34:49], v[78:81], v[98:101], v[34:49]
	v_bfe_i32 v73, v67, 9, 1
	v_bfe_i32 v78, v67, 18, 1
	v_bfe_i32 v79, v67, 19, 1
	v_bfe_i32 v80, v67, 24, 1
	v_bfe_i32 v81, v67, 25, 1
	v_mov_b64_e32 v[52:53], v[4:5]
	v_mov_b64_e32 v[50:51], v[2:3]
	v_mfma_f32_32x32x16_bf16 v[18:33], v[74:77], v[102:105], v[18:33]
	s_nop 3
	v_bitop3_b32 v68, v34, s74, v68 bitop3:0xe4
	v_bfe_i32 v34, v66, 1, 1
	v_bitop3_b32 v35, v35, s74, v34 bitop3:0xe4
	v_bfe_i32 v34, v66, 2, 1
	v_bitop3_b32 v36, v36, s74, v34 bitop3:0xe4
	v_bfe_i32 v34, v66, 3, 1
	v_bitop3_b32 v37, v37, s74, v34 bitop3:0xe4
	v_bfe_i32 v34, v66, 8, 1
	v_bitop3_b32 v38, v38, s74, v34 bitop3:0xe4
	v_bfe_i32 v34, v66, 9, 1
	v_bitop3_b32 v39, v39, s74, v34 bitop3:0xe4
	v_bfe_i32 v34, v66, 10, 1
	v_bitop3_b32 v40, v40, s74, v34 bitop3:0xe4
	v_bfe_i32 v34, v66, 11, 1
	v_mfma_f32_32x32x16_bf16 v[18:33], v[82:85], v[98:101], v[18:33]
	v_bitop3_b32 v41, v41, s74, v34 bitop3:0xe4
	v_bfe_i32 v34, v66, 16, 1
	v_bitop3_b32 v42, v42, s74, v34 bitop3:0xe4
	v_bfe_i32 v34, v66, 17, 1
	v_bitop3_b32 v43, v43, s74, v34 bitop3:0xe4
	v_bfe_i32 v34, v66, 18, 1
	v_bitop3_b32 v44, v44, s74, v34 bitop3:0xe4
	v_bfe_i32 v34, v66, 19, 1
	v_bitop3_b32 v45, v45, s74, v34 bitop3:0xe4
	v_bfe_i32 v34, v66, 24, 1
	v_bitop3_b32 v46, v46, s74, v34 bitop3:0xe4
	v_bfe_i32 v34, v66, 25, 1
	v_bitop3_b32 v47, v47, s74, v34 bitop3:0xe4
	v_bfe_i32 v34, v66, 26, 1
	v_bitop3_b32 v48, v48, s74, v34 bitop3:0xe4
	v_bfe_i32 v34, v66, 27, 1
	v_bitop3_b32 v18, v18, s74, v69 bitop3:0xe4
	v_bfe_i32 v69, v67, 1, 1
	v_bfe_i32 v74, v67, 10, 1
	v_bfe_i32 v75, v67, 11, 1
	v_bfe_i32 v76, v67, 16, 1
	v_bfe_i32 v77, v67, 17, 1
	v_bfe_i32 v82, v67, 26, 1
	v_bfe_i32 v66, v67, 27, 1
	v_bitop3_b32 v49, v49, s74, v34 bitop3:0xe4
	v_max_f32_e32 v34, v35, v35
	v_max_f32_e32 v67, v68, v68
	v_max_f32_e32 v34, v67, v34
	v_max3_f32 v34, v34, v36, v37
	v_max3_f32 v34, v34, v38, v39
	v_max3_f32 v34, v34, v40, v41
	v_max3_f32 v34, v34, v42, v43
	v_max3_f32 v34, v34, v44, v45
	v_max3_f32 v34, v34, v46, v47
	v_max3_f32 v34, v34, v48, v49
	v_bitop3_b32 v19, v19, s74, v69 bitop3:0xe4
	v_bitop3_b32 v20, v20, s74, v70 bitop3:0xe4
	v_max3_f32 v34, v34, v18, v19
	v_bitop3_b32 v21, v21, s74, v71 bitop3:0xe4
	v_bitop3_b32 v22, v22, s74, v72 bitop3:0xe4
	v_max3_f32 v34, v34, v20, v21
	v_bitop3_b32 v23, v23, s74, v73 bitop3:0xe4
	v_bitop3_b32 v24, v24, s74, v74 bitop3:0xe4
	v_max3_f32 v34, v34, v22, v23
	v_bitop3_b32 v25, v25, s74, v75 bitop3:0xe4
	v_bitop3_b32 v26, v26, s74, v76 bitop3:0xe4
	v_max3_f32 v34, v34, v24, v25
	v_bitop3_b32 v27, v27, s74, v77 bitop3:0xe4
	v_bitop3_b32 v28, v28, s74, v78 bitop3:0xe4
	v_max3_f32 v34, v34, v26, v27
	v_bitop3_b32 v29, v29, s74, v79 bitop3:0xe4
	v_bitop3_b32 v30, v30, s74, v80 bitop3:0xe4
	v_max3_f32 v34, v34, v28, v29
	v_bitop3_b32 v31, v31, s74, v81 bitop3:0xe4
	v_bitop3_b32 v32, v32, s74, v82 bitop3:0xe4
	v_max3_f32 v34, v34, v30, v31
	v_bitop3_b32 v33, v33, s74, v66 bitop3:0xe4
	v_max3_f32 v34, v34, v32, v33
	v_mov_b32_e32 v66, v34
	s_nop 1
	v_permlane32_swap_b32_e32 v34, v66
	v_max_f32_e32 v66, v66, v66
	v_max_f32_e32 v34, v34, v34
	v_max_f32_e32 v34, v34, v66
	v_add_f32_e32 v66, 0x7149f2ca, v34
	v_mul_f32_e32 v66, 0x3db504f3, v66
	v_max_f32_e32 v34, 0xf149f2ca, v34
	v_cmp_ge_f32_e32 vcc, s75, v66
	v_sub_f32_e32 v66, 0xf149f2ca, v34
	v_mul_f32_e32 v66, 0x3e0293ee, v66
	s_cmp_eq_u64 vcc, exec
	v_exp_f32_e32 v66, v66
	s_cselect_b64 vcc, -1, 0
	v_cndmask_b32_e32 v206, v34, v203, vcc
	v_mul_f32_e32 v34, 0xbe0293ee, v206
	v_mov_b32_e32 v67, v34
	v_cndmask_b32_e64 v177, v66, 1.0, vcc
	v_fmamk_f32 v66, v68, 0x3e0293ee, v34
	v_fmamk_f32 v35, v35, 0x3e0293ee, v34
	v_fmamk_f32 v36, v36, 0x3e0293ee, v34
	v_fmamk_f32 v37, v37, 0x3e0293ee, v34
	v_fmamk_f32 v38, v38, 0x3e0293ee, v34
	v_fmamk_f32 v39, v39, 0x3e0293ee, v34
	v_fmamk_f32 v40, v40, 0x3e0293ee, v34
	v_fmamk_f32 v41, v41, 0x3e0293ee, v34
	v_fmamk_f32 v42, v42, 0x3e0293ee, v34
	v_fmamk_f32 v43, v43, 0x3e0293ee, v34
	v_fmamk_f32 v44, v44, 0x3e0293ee, v34
	v_fmamk_f32 v45, v45, 0x3e0293ee, v34
	v_fmamk_f32 v46, v46, 0x3e0293ee, v34
	v_fmamk_f32 v47, v47, 0x3e0293ee, v34
	v_fmamk_f32 v48, v48, 0x3e0293ee, v34
	v_fmac_f32_e32 v67, 0x3e0293ee, v49
	v_exp_f32_e32 v219, v66
	v_exp_f32_e32 v220, v35
	v_exp_f32_e32 v221, v36
	v_exp_f32_e32 v222, v37
	v_exp_f32_e32 v223, v38
	v_exp_f32_e32 v225, v39
	v_exp_f32_e32 v224, v40
	v_exp_f32_e32 v226, v41
	v_exp_f32_e32 v211, v42
	v_exp_f32_e32 v212, v43
	v_exp_f32_e32 v213, v44
	v_exp_f32_e32 v215, v45
	v_exp_f32_e32 v214, v46
	v_exp_f32_e32 v216, v47
	v_exp_f32_e32 v217, v48
	v_exp_f32_e32 v218, v67
	s_lshl_b32 s36, s83, 8
	v_pk_fma_f32 v[152:153], v[32:33], s[14:15], v[34:35] op_sel_hi:[1,0,0]
	v_pk_fma_f32 v[156:157], v[30:31], s[14:15], v[34:35] op_sel_hi:[1,0,0]
	v_pk_fma_f32 v[160:161], v[28:29], s[14:15], v[34:35] op_sel_hi:[1,0,0]
	v_pk_fma_f32 v[150:151], v[26:27], s[14:15], v[34:35] op_sel_hi:[1,0,0]
	v_pk_fma_f32 v[154:155], v[24:25], s[14:15], v[34:35] op_sel_hi:[1,0,0]
	v_pk_fma_f32 v[158:159], v[22:23], s[14:15], v[34:35] op_sel_hi:[1,0,0]
	v_pk_fma_f32 v[192:193], v[20:21], s[14:15], v[34:35] op_sel_hi:[1,0,0]
	v_pk_fma_f32 v[194:195], v[18:19], s[14:15], v[34:35] op_sel_hi:[1,0,0]
	s_and_b32 s36, s36, 0xffffc000
	v_mov_b64_e32 v[48:49], v[16:17]
	v_mov_b64_e32 v[32:33], v[16:17]
	v_or_b32_e32 v179, s36, v254
	v_mov_b64_e32 v[46:47], v[14:15]
	v_mov_b64_e32 v[44:45], v[12:13]
	v_mov_b64_e32 v[42:43], v[10:11]
	v_mov_b64_e32 v[40:41], v[8:9]
	v_mov_b64_e32 v[38:39], v[6:7]
	v_mov_b64_e32 v[36:37], v[4:5]
	v_mov_b64_e32 v[34:35], v[2:3]
	v_mov_b64_e32 v[30:31], v[14:15]
	v_mov_b64_e32 v[28:29], v[12:13]
	v_mov_b64_e32 v[26:27], v[10:11]
	v_mov_b64_e32 v[24:25], v[8:9]
	v_mov_b64_e32 v[22:23], v[6:7]
	v_mov_b64_e32 v[20:21], v[4:5]
	v_mov_b64_e32 v[18:19], v[2:3]
	v_mul_f32_e32 v190, 0xbe0293ee, v206

; #define SBAR() __builtin_amdgcn_sched_barrier(0)
; #define VMW() asm volatile("s_waitcnt vmcnt(0)" ::: "memory")
; #define SLOAD_H(Kp, Vp, k0) do { S.st_v0 = load8(ROW(Vp, k0, sr)); S.st_v1 = load8(ROW(Vp, k0, 32 + sr));              \
;                          S.st_k0 = load8(ROW(Kp, k0, sr)); S.st_k1 = load8(ROW(Kp, k0, 32 + sr)); } while (0)
; #define SWRITE_HV(bf) do { *(bf16x8*)(V_lds + (bf) * SHM_V + vst0) = S.st_v0; *(bf16x8*)(V_lds + (bf) * SHM_V + vst1) = S.st_v1; } while (0)
; #define SWRITE_H(bf) do { SWRITE_HV(bf); SWRITE_HK(bf); } while (0)
; #define MASKT(P0_, P1_) sel_mask_tile(P0_, P1_, mw.x, mw.y, hi)
; __device__ __forceinline__ void partialSM(f32x16& p0, f32x16& p1, float& m_reg, float& mn, float& alpha) {
;     ...
;     constexpr float C2 = 1.4426950408889634f * SCALE;
;     if (__builtin_expect(__all((pmax - m_reg) * SCALE <= THR), 1)) { mn = m_reg; alpha = 1.f; }
;     else { mn = fmaxf(m_reg, pmax); alpha = __builtin_amdgcn_exp2f((m_reg - mn) * C2); m_reg = mn; }
;     const float mnL = -mn * C2;
; #pragma unroll
;     for (int r = 0; r < 16; ++r) p0[r] = fmaf(p0[r], C2, mnL);
; #pragma unroll
;     for (int r = 0; r < 16; ++r) p1[r] = fmaf(p1[r], C2, mnL);
; #pragma unroll
;     for (int r = 0; r < 16; ++r) p0[r] = __builtin_amdgcn_exp2f(p0[r]);
; __device__ __forceinline__ void attn_block(const BlockRef& cur, const BlockRef& nxt, char* lds, Seam& S) {
;     ...
;     constexpr int NQL = 8;
;     ...
;     f32x16 pA0, pA1, pB0, pB1; float mnA, mnB, alA, alB; bf16x8 pa0, pa1, pa2, pa3;
;     SWRITE_HV(0); SBAR();
;     mw = LDMASK(0);
;     if (NT > 1) { SLOAD_H(Kh, Vh, KBASE(1)); }
;     SBAR(); qkt<0>(pA0, pA1, K_lds, r32, hi, S.qr);
;     MASKT(pA0, pA1); partialSM(pA0, pA1, m_reg, mnA, alA);
;     if (NT > 1) { VMW(); SWRITE_H(1); }
;     __syncthreads();
.Lp5_b1fast:
	s_barrier
	s_waitcnt vmcnt(0)
	v_cndmask_b32_e64 v208, v96, 1.0, s[6:7]
	s_not_b64 vcc, s[6:7]
	ds_write_b128 v197, v[130:133]
	ds_write_b128 v198, v[134:137]
	s_cbranch_vccz .LBB0_1303
	v_mov_b32_e32 v206, v94
	v_mul_f32_e32 v190, 0xbe0293ee, v94
	s_and_saveexec_b64 s[36:37], s[0:1]
	ds_write_b32 v185, v208 offset:128
	s_or_b64 exec, exec, s[36:37]
	s_waitcnt lgkmcnt(0)
	ds_read_b128 v[150:153], v183 offset:224
	ds_read_b128 v[154:157], v183 offset:192
	ds_read_b128 v[158:161], v183 offset:160
	ds_read_b128 v[172:175], v183 offset:128
	s_waitcnt lgkmcnt(3)
	v_pk_mul_f32 v[16:17], v[16:17], v[152:153]
	s_waitcnt lgkmcnt(2)
	v_pk_mul_f32 v[12:13], v[12:13], v[156:157]
	s_waitcnt lgkmcnt(1)
	v_pk_mul_f32 v[8:9], v[8:9], v[160:161]
	s_waitcnt lgkmcnt(0)
	v_pk_mul_f32 v[4:5], v[4:5], v[174:175]
	v_pk_mul_f32 v[14:15], v[14:15], v[150:151]
	v_pk_mul_f32 v[10:11], v[10:11], v[154:155]
	v_pk_mul_f32 v[6:7], v[6:7], v[158:159]
	v_pk_mul_f32 v[2:3], v[2:3], v[172:173]
	v_pk_mul_f32 v[64:65], v[64:65], v[152:153]
	v_pk_mul_f32 v[60:61], v[60:61], v[156:157]
	v_pk_mul_f32 v[56:57], v[56:57], v[160:161]
	v_pk_mul_f32 v[52:53], v[52:53], v[174:175]
	v_pk_mul_f32 v[62:63], v[62:63], v[150:151]
	v_pk_mul_f32 v[58:59], v[58:59], v[154:155]
	v_pk_mul_f32 v[54:55], v[54:55], v[158:159]
	v_pk_mul_f32 v[50:51], v[50:51], v[172:173]
	v_pk_mul_f32 v[48:49], v[48:49], v[152:153]
	v_pk_mul_f32 v[44:45], v[44:45], v[156:157]
	v_pk_mul_f32 v[40:41], v[40:41], v[160:161]
	v_pk_mul_f32 v[36:37], v[36:37], v[174:175]
	v_pk_mul_f32 v[46:47], v[46:47], v[150:151]
	v_pk_mul_f32 v[42:43], v[42:43], v[154:155]
	v_pk_mul_f32 v[38:39], v[38:39], v[158:159]
	v_pk_mul_f32 v[34:35], v[34:35], v[172:173]
	v_pk_mul_f32 v[32:33], v[32:33], v[152:153]
	v_pk_mul_f32 v[28:29], v[28:29], v[156:157]
	v_pk_mul_f32 v[24:25], v[24:25], v[160:161]
	v_pk_mul_f32 v[20:21], v[20:21], v[174:175]
	v_pk_mul_f32 v[30:31], v[30:31], v[150:151]
	v_pk_mul_f32 v[26:27], v[26:27], v[154:155]
	v_pk_mul_f32 v[22:23], v[22:23], v[158:159]
	v_pk_mul_f32 v[18:19], v[18:19], v[172:173]
.LBB0_1303:
	v_fmamk_f32 v94, v146, 0x3e0293ee, v190
	v_fmamk_f32 v82, v82, 0x3e0293ee, v190
	v_fmamk_f32 v83, v83, 0x3e0293ee, v190
	v_fmamk_f32 v95, v147, 0x3e0293ee, v190
	v_fmamk_f32 v96, v148, 0x3e0293ee, v190
	v_fmamk_f32 v97, v149, 0x3e0293ee, v190
	v_fmamk_f32 v87, v87, 0x3e0293ee, v190
	v_fmamk_f32 v88, v88, 0x3e0293ee, v190
	v_fmamk_f32 v89, v89, 0x3e0293ee, v190
	v_fmamk_f32 v90, v90, 0x3e0293ee, v190
	v_fmamk_f32 v91, v91, 0x3e0293ee, v190
	v_fmamk_f32 v92, v92, 0x3e0293ee, v190
	v_fmamk_f32 v93, v93, 0x3e0293ee, v190
	v_fmamk_f32 v79, v79, 0x3e0293ee, v190
	v_fmamk_f32 v80, v80, 0x3e0293ee, v190
	v_fmamk_f32 v81, v81, 0x3e0293ee, v190
	v_exp_f32_e32 v146, v94
	v_exp_f32_e32 v147, v82
	v_exp_f32_e32 v148, v83
	v_exp_f32_e32 v159, v95
	v_exp_f32_e32 v160, v96
	v_exp_f32_e32 v161, v97
	v_exp_f32_e32 v149, v87
	v_exp_f32_e32 v158, v88
	v_exp_f32_e32 v150, v89
	v_exp_f32_e32 v151, v90
	v_exp_f32_e32 v155, v91
	v_exp_f32_e32 v157, v92
	v_exp_f32_e32 v152, v93
	v_exp_f32_e32 v153, v79
	v_exp_f32_e32 v154, v80
	v_exp_f32_e32 v156, v81
	v_fmamk_f32 v210, v71, 0x3e0293ee, v190
	v_fmamk_f32 v209, v78, 0x3e0293ee, v190
	v_fmamk_f32 v217, v66, 0x3e0293ee, v190
	v_fmamk_f32 v218, v67, 0x3e0293ee, v190
	v_fmamk_f32 v219, v68, 0x3e0293ee, v190
	v_fmamk_f32 v220, v69, 0x3e0293ee, v190
	v_fmamk_f32 v221, v70, 0x3e0293ee, v190
	v_fmamk_f32 v211, v72, 0x3e0293ee, v190
	v_fmamk_f32 v212, v84, 0x3e0293ee, v190
	v_fmamk_f32 v213, v85, 0x3e0293ee, v190
	v_fmamk_f32 v214, v86, 0x3e0293ee, v190
	v_fmamk_f32 v215, v76, 0x3e0293ee, v190
	v_fmamk_f32 v216, v77, 0x3e0293ee, v190
	v_fmamk_f32 v222, v73, 0x3e0293ee, v190
	v_fmamk_f32 v223, v74, 0x3e0293ee, v190
	v_fmamk_f32 v207, v75, 0x3e0293ee, v190
	s_waitcnt lgkmcnt(0)
	s_barrier
	global_load_dwordx2 v[228:229], v179, s[68:69]
	s_add_i32 s98, s82, 2
	s_cmp_gt_u32 s98, s81
	s_cbranch_scc1 .Lp5_a2
	s_add_u32 s98, s16, 0x60000
	s_addc_u32 s99, s17, 0
	global_load_dwordx4 v[130:133], v188, s[98:99]
	s_add_u32 s98, s16, 0x70000
	s_addc_u32 s99, s17, 0
	global_load_dwordx4 v[134:137], v188, s[98:99]
	s_add_u32 s98, s100, 0x60000
	s_addc_u32 s99, s101, 0
	global_load_dwordx4 v[138:141], v188, s[98:99]
	s_add_u32 s98, s100, 0x70000
	s_addc_u32 s99, s101, 0
	global_load_dwordx4 v[142:145], v188, s[98:99]

; #define SBAR() __builtin_amdgcn_sched_barrier(0)
; #define VMW() asm volatile("s_waitcnt vmcnt(0)" ::: "memory")
; #define SLOAD_H(Kp, Vp, k0) do { S.st_v0 = load8(ROW(Vp, k0, sr)); S.st_v1 = load8(ROW(Vp, k0, 32 + sr));              \
;                          S.st_k0 = load8(ROW(Kp, k0, sr)); S.st_k1 = load8(ROW(Kp, k0, 32 + sr)); } while (0)
; #define SWRITE_HV(bf) do { *(bf16x8*)(V_lds + (bf) * SHM_V + vst0) = S.st_v0; *(bf16x8*)(V_lds + (bf) * SHM_V + vst1) = S.st_v1; } while (0)
; #define SWRITE_H(bf) do { SWRITE_HV(bf); SWRITE_HK(bf); } while (0)
; #define MASKT(P0_, P1_) sel_mask_tile(P0_, P1_, mw.x, mw.y, hi)
; __device__ __forceinline__ void partialSM(f32x16& p0, f32x16& p1, float& m_reg, float& mn, float& alpha) {
;     ...
;     constexpr float C2 = 1.4426950408889634f * SCALE;
;     if (__builtin_expect(__all((pmax - m_reg) * SCALE <= THR), 1)) { mn = m_reg; alpha = 1.f; }
;     else { mn = fmaxf(m_reg, pmax); alpha = __builtin_amdgcn_exp2f((m_reg - mn) * C2); m_reg = mn; }
;     const float mnL = -mn * C2;
; #pragma unroll
;     for (int r = 0; r < 16; ++r) p0[r] = fmaf(p0[r], C2, mnL);
; #pragma unroll
;     for (int r = 0; r < 16; ++r) p1[r] = fmaf(p1[r], C2, mnL);
; #pragma unroll
;     for (int r = 0; r < 16; ++r) p0[r] = __builtin_amdgcn_exp2f(p0[r]);
; __device__ __forceinline__ void attn_block(const BlockRef& cur, const BlockRef& nxt, char* lds, Seam& S) {
;     ...
;     constexpr int NQL = 8;
;     ...
;     f32x16 pA0, pA1, pB0, pB1; float mnA, mnB, alA, alB; bf16x8 pa0, pa1, pa2, pa3;
;     SWRITE_HV(0); SBAR();
;     mw = LDMASK(0);
;     if (NT > 1) { SLOAD_H(Kh, Vh, KBASE(1)); }
;     SBAR(); qkt<0>(pA0, pA1, K_lds, r32, hi, S.qr);
;     MASKT(pA0, pA1); partialSM(pA0, pA1, m_reg, mnA, alA);
;     if (NT > 1) { VMW(); SWRITE_H(1); }
;     __syncthreads();
;     ...
;     for (int t = 1; t + 1 < NT; t += 2) {
;         HALF_STEP(pB0, pB1, mnB, alB, pA0, pA1, alA, t, 1, 0, 0);
;         HALF_STEP(pA0, pA1, mnA, alA, pB0, pB1, alB, t + 1, 0, 1, 1);
;     }
.LBB0_1307:
	v_mov_b32_e32 v207, 1.0
	s_not_b64 vcc, s[6:7]
	s_cbranch_vccz .LBB0_1311
	v_max_f32_e32 v76, v206, v76
	v_sub_f32_e32 v77, v206, v76
	v_mul_f32_e32 v77, 0x3e0293ee, v77
	v_exp_f32_e32 v77, v77
	s_nop 0
	v_cndmask_b32_e64 v207, v77, 1.0, s[6:7]
	v_mov_b32_e32 v206, v76
	v_mul_f32_e32 v190, 0xbe0293ee, v76
	s_and_saveexec_b64 s[36:37], s[0:1]
	ds_write_b32 v185, v207 offset:128
	s_or_b64 exec, exec, s[36:37]
	s_waitcnt lgkmcnt(0)
	ds_read_b128 v[78:81], v183 offset:224
	ds_read_b128 v[130:133], v183 offset:192
	ds_read_b128 v[134:137], v183 offset:160
	ds_read_b128 v[138:141], v183 offset:128
	s_waitcnt lgkmcnt(3)
	v_pk_mul_f32 v[16:17], v[16:17], v[80:81]
	s_waitcnt lgkmcnt(2)
	v_pk_mul_f32 v[12:13], v[12:13], v[132:133]
	s_waitcnt lgkmcnt(1)
	v_pk_mul_f32 v[8:9], v[8:9], v[136:137]
	s_waitcnt lgkmcnt(0)
	v_pk_mul_f32 v[4:5], v[4:5], v[140:141]
	v_pk_mul_f32 v[14:15], v[14:15], v[78:79]
	v_pk_mul_f32 v[10:11], v[10:11], v[130:131]
	v_pk_mul_f32 v[6:7], v[6:7], v[134:135]
	v_pk_mul_f32 v[2:3], v[2:3], v[138:139]
	v_pk_mul_f32 v[64:65], v[64:65], v[80:81]
	v_pk_mul_f32 v[60:61], v[60:61], v[132:133]
	v_pk_mul_f32 v[56:57], v[56:57], v[136:137]
	v_pk_mul_f32 v[52:53], v[52:53], v[140:141]
	v_pk_mul_f32 v[62:63], v[62:63], v[78:79]
	v_pk_mul_f32 v[58:59], v[58:59], v[130:131]
	v_pk_mul_f32 v[54:55], v[54:55], v[134:135]
	v_pk_mul_f32 v[50:51], v[50:51], v[138:139]
	v_pk_mul_f32 v[48:49], v[48:49], v[80:81]
	v_pk_mul_f32 v[44:45], v[44:45], v[132:133]
	v_pk_mul_f32 v[40:41], v[40:41], v[136:137]
	v_pk_mul_f32 v[36:37], v[36:37], v[140:141]
	v_pk_mul_f32 v[46:47], v[46:47], v[78:79]
	v_pk_mul_f32 v[42:43], v[42:43], v[130:131]
	v_pk_mul_f32 v[38:39], v[38:39], v[134:135]
	v_pk_mul_f32 v[34:35], v[34:35], v[138:139]
	v_pk_mul_f32 v[32:33], v[32:33], v[80:81]
	v_pk_mul_f32 v[28:29], v[28:29], v[132:133]
	v_pk_mul_f32 v[24:25], v[24:25], v[136:137]
	v_pk_mul_f32 v[20:21], v[20:21], v[140:141]
	v_pk_mul_f32 v[30:31], v[30:31], v[78:79]
	v_pk_mul_f32 v[26:27], v[26:27], v[130:131]
	v_pk_mul_f32 v[22:23], v[22:23], v[134:135]
	v_pk_mul_f32 v[18:19], v[18:19], v[138:139]
.LBB0_1311:
	v_fmamk_f32 v77, v192, 0x3e0293ee, v190
	v_fmamk_f32 v78, v146, 0x3e0293ee, v190
	v_fmamk_f32 v79, v147, 0x3e0293ee, v190
	v_fmamk_f32 v80, v148, 0x3e0293ee, v190
	v_fmamk_f32 v81, v149, 0x3e0293ee, v190
	v_fmamk_f32 v130, v150, 0x3e0293ee, v190
	v_fmamk_f32 v88, v88, 0x3e0293ee, v190
	v_fmamk_f32 v89, v89, 0x3e0293ee, v190
	v_fmamk_f32 v90, v90, 0x3e0293ee, v190
	v_fmamk_f32 v91, v91, 0x3e0293ee, v190
	v_fmamk_f32 v92, v92, 0x3e0293ee, v190
	v_fmamk_f32 v93, v93, 0x3e0293ee, v190
	v_fmamk_f32 v94, v94, 0x3e0293ee, v190
	v_fmamk_f32 v95, v95, 0x3e0293ee, v190
	v_fmamk_f32 v96, v96, 0x3e0293ee, v190
	v_fmamk_f32 v131, v97, 0x3e0293ee, v190
	v_exp_f32_e32 v219, v77
	v_exp_f32_e32 v220, v78
	v_exp_f32_e32 v221, v79
	v_exp_f32_e32 v222, v80
	v_exp_f32_e32 v223, v81
	v_exp_f32_e32 v225, v130
	v_exp_f32_e32 v224, v88
	v_exp_f32_e32 v226, v89
	v_exp_f32_e32 v211, v90
	v_exp_f32_e32 v212, v91
	v_exp_f32_e32 v213, v92
	v_exp_f32_e32 v215, v93
	v_exp_f32_e32 v214, v94
	v_exp_f32_e32 v216, v95
	v_exp_f32_e32 v217, v96
	v_exp_f32_e32 v218, v131
	v_pk_fma_f32 v[194:195], v[66:67], s[14:15], v[190:191] op_sel_hi:[1,0,0]
	v_fmac_f32_e32 v181, v177, v205
	v_pk_fma_f32 v[192:193], v[82:83], s[14:15], v[190:191] op_sel_hi:[1,0,0]
	v_pk_fma_f32 v[158:159], v[84:85], s[14:15], v[190:191] op_sel_hi:[1,0,0]
	v_pk_fma_f32 v[154:155], v[86:87], s[14:15], v[190:191] op_sel_hi:[1,0,0]
	v_pk_fma_f32 v[150:151], v[74:75], s[14:15], v[190:191] op_sel_hi:[1,0,0]
	v_pk_fma_f32 v[160:161], v[68:69], s[14:15], v[190:191] op_sel_hi:[1,0,0]
	v_pk_fma_f32 v[156:157], v[70:71], s[14:15], v[190:191] op_sel_hi:[1,0,0]
	v_pk_fma_f32 v[152:153], v[72:73], s[14:15], v[190:191] op_sel_hi:[1,0,0]
	v_fma_f32 v205, v181, v208, v209
	v_add_u32_e32 v179, 16, v179
	s_add_u32 s16, s16, 0x40000
	s_addc_u32 s17, s17, 0
	s_add_u32 s100, s100, 0x40000
	s_addc_u32 s101, s101, 0
	s_cmp_ge_u32 s82, s81
	s_waitcnt lgkmcnt(0)
	s_barrier
	s_cbranch_scc1 .LBB0_1313
	v_mov_b32_e32 v177, v207
	s_branch .LBB0_1299
